# write-through (sc1) stores for P6 Y tile and P8 H2 rows so the barrier L2 write-back has nothing left to flush
# speedup vs baseline: 1.0016x; 1.0016x over previous
.Lp6e_bz1:
	global_load_dwordx4 v[154:157], v240, s[64:65]
	global_load_dwordx4 v[190:193], v240, s[94:95]
	global_load_dwordx4 v[158:161], v240, s[64:65] offset:256
	global_load_dwordx4 v[194:197], v240, s[94:95] offset:256
	global_load_dwordx4 v[162:165], v241, s[64:65]
	global_load_dwordx4 v[198:201], v241, s[94:95]
	global_load_dwordx4 v[166:169], v241, s[64:65] offset:256
	global_load_dwordx4 v[202:205], v241, s[94:95] offset:256
	global_load_dwordx4 v[170:173], v242, s[64:65]
	global_load_dwordx4 v[206:209], v242, s[94:95]
	global_load_dwordx4 v[174:177], v242, s[64:65] offset:256
	global_load_dwordx4 v[210:213], v242, s[94:95] offset:256
	global_load_dwordx4 v[178:181], v243, s[64:65]
	global_load_dwordx4 v[214:217], v243, s[94:95]
	global_load_dwordx4 v[182:185], v243, s[64:65] offset:256
	global_load_dwordx4 v[230:233], v243, s[94:95] offset:256
	s_waitcnt vmcnt(14)
	v_permlane16_swap_b32_e32 v154, v156
	v_permlane16_swap_b32_e32 v155, v157
	v_permlane16_swap_b32_e32 v190, v192
	v_permlane16_swap_b32_e32 v191, v193
	v_lshlrev_b32_e32 v136, 16, v154
	v_and_b32_e32 v137, 0xffff0000, v154
	v_lshlrev_b32_e32 v138, 16, v155
	v_and_b32_e32 v139, 0xffff0000, v155
	v_lshlrev_b32_e32 v140, 16, v156
	v_and_b32_e32 v141, 0xffff0000, v156
	v_lshlrev_b32_e32 v142, 16, v157
	v_and_b32_e32 v143, 0xffff0000, v157
	v_lshlrev_b32_e32 v144, 16, v190
	v_and_b32_e32 v145, 0xffff0000, v190
	v_lshlrev_b32_e32 v146, 16, v191
	v_and_b32_e32 v147, 0xffff0000, v191
	v_lshlrev_b32_e32 v234, 16, v192
	v_and_b32_e32 v235, 0xffff0000, v192
	v_lshlrev_b32_e32 v236, 16, v193
	v_and_b32_e32 v237, 0xffff0000, v193
	global_load_dwordx4 v[154:157], v244, s[64:65]
	global_load_dwordx4 v[190:193], v244, s[94:95]
	v_pk_fma_f32 v[124:125], v[124:125], v[144:145], v[136:137]
	v_pk_fma_f32 v[126:127], v[126:127], v[146:147], v[138:139]
	v_pk_fma_f32 v[120:121], v[120:121], v[234:235], v[140:141]
	v_pk_fma_f32 v[122:123], v[122:123], v[236:237], v[142:143]
	s_nop 0
	v_cvt_pk_bf16_f32 v124, v124, v125
	v_cvt_pk_bf16_f32 v125, v126, v127
	v_cvt_pk_bf16_f32 v126, v120, v121
	v_cvt_pk_bf16_f32 v127, v122, v123
	s_nop 1
	v_permlane16_swap_b32_e32 v124, v126
	v_permlane16_swap_b32_e32 v125, v127
	global_store_dwordx4 v240, v[124:127], s[90:91] sc1
	s_waitcnt vmcnt(15)
	v_permlane16_swap_b32_e32 v158, v160
	v_permlane16_swap_b32_e32 v159, v161
	v_permlane16_swap_b32_e32 v194, v196
	v_permlane16_swap_b32_e32 v195, v197
	v_lshlrev_b32_e32 v136, 16, v158
	v_and_b32_e32 v137, 0xffff0000, v158
	v_lshlrev_b32_e32 v138, 16, v159
	v_and_b32_e32 v139, 0xffff0000, v159
	v_lshlrev_b32_e32 v140, 16, v160
	v_and_b32_e32 v141, 0xffff0000, v160
	v_lshlrev_b32_e32 v142, 16, v161
	v_and_b32_e32 v143, 0xffff0000, v161
	v_lshlrev_b32_e32 v144, 16, v194
	v_and_b32_e32 v145, 0xffff0000, v194
	v_lshlrev_b32_e32 v146, 16, v195
	v_and_b32_e32 v147, 0xffff0000, v195
	v_lshlrev_b32_e32 v234, 16, v196
	v_and_b32_e32 v235, 0xffff0000, v196
	v_lshlrev_b32_e32 v236, 16, v197
	v_and_b32_e32 v237, 0xffff0000, v197
	global_load_dwordx4 v[158:161], v244, s[64:65] offset:256
	global_load_dwordx4 v[194:197], v244, s[94:95] offset:256
	v_pk_fma_f32 v[116:117], v[116:117], v[144:145], v[136:137]
	v_pk_fma_f32 v[118:119], v[118:119], v[146:147], v[138:139]
	v_pk_fma_f32 v[112:113], v[112:113], v[234:235], v[140:141]
	v_pk_fma_f32 v[114:115], v[114:115], v[236:237], v[142:143]
	s_nop 0
	v_cvt_pk_bf16_f32 v116, v116, v117
	v_cvt_pk_bf16_f32 v117, v118, v119
	v_cvt_pk_bf16_f32 v118, v112, v113
	v_cvt_pk_bf16_f32 v119, v114, v115
	s_nop 1
	v_permlane16_swap_b32_e32 v116, v118
	v_permlane16_swap_b32_e32 v117, v119
	global_store_dwordx4 v240, v[116:119], s[90:91] offset:256 sc1
	s_waitcnt vmcnt(16)
	v_permlane16_swap_b32_e32 v162, v164
	v_permlane16_swap_b32_e32 v163, v165
	v_permlane16_swap_b32_e32 v198, v200
	v_permlane16_swap_b32_e32 v199, v201
	v_lshlrev_b32_e32 v136, 16, v162
	v_and_b32_e32 v137, 0xffff0000, v162
	v_lshlrev_b32_e32 v138, 16, v163
	v_and_b32_e32 v139, 0xffff0000, v163
	v_lshlrev_b32_e32 v140, 16, v164
	v_and_b32_e32 v141, 0xffff0000, v164
	v_lshlrev_b32_e32 v142, 16, v165
	v_and_b32_e32 v143, 0xffff0000, v165
	v_lshlrev_b32_e32 v144, 16, v198
	v_and_b32_e32 v145, 0xffff0000, v198
	v_lshlrev_b32_e32 v146, 16, v199
	v_and_b32_e32 v147, 0xffff0000, v199
	v_lshlrev_b32_e32 v234, 16, v200
	v_and_b32_e32 v235, 0xffff0000, v200
	v_lshlrev_b32_e32 v236, 16, v201
	v_and_b32_e32 v237, 0xffff0000, v201
	global_load_dwordx4 v[162:165], v245, s[64:65]
	global_load_dwordx4 v[198:201], v245, s[94:95]
	v_pk_fma_f32 v[108:109], v[108:109], v[144:145], v[136:137]
	v_pk_fma_f32 v[110:111], v[110:111], v[146:147], v[138:139]
	v_pk_fma_f32 v[104:105], v[104:105], v[234:235], v[140:141]
	v_pk_fma_f32 v[106:107], v[106:107], v[236:237], v[142:143]
	s_nop 0
	v_cvt_pk_bf16_f32 v108, v108, v109
	v_cvt_pk_bf16_f32 v109, v110, v111
	v_cvt_pk_bf16_f32 v110, v104, v105
	v_cvt_pk_bf16_f32 v111, v106, v107
	s_nop 1
	v_permlane16_swap_b32_e32 v108, v110
	v_permlane16_swap_b32_e32 v109, v111
	global_store_dwordx4 v241, v[108:111], s[90:91] sc1
	s_waitcnt vmcnt(17)
	v_permlane16_swap_b32_e32 v166, v168
	v_permlane16_swap_b32_e32 v167, v169
	v_permlane16_swap_b32_e32 v202, v204
	v_permlane16_swap_b32_e32 v203, v205
	v_lshlrev_b32_e32 v136, 16, v166
	v_and_b32_e32 v137, 0xffff0000, v166
	v_lshlrev_b32_e32 v138, 16, v167
	v_and_b32_e32 v139, 0xffff0000, v167
	v_lshlrev_b32_e32 v140, 16, v168
	v_and_b32_e32 v141, 0xffff0000, v168
	v_lshlrev_b32_e32 v142, 16, v169
	v_and_b32_e32 v143, 0xffff0000, v169
	v_lshlrev_b32_e32 v144, 16, v202
	v_and_b32_e32 v145, 0xffff0000, v202
	v_lshlrev_b32_e32 v146, 16, v203
	v_and_b32_e32 v147, 0xffff0000, v203
	v_lshlrev_b32_e32 v234, 16, v204
	v_and_b32_e32 v235, 0xffff0000, v204
	v_lshlrev_b32_e32 v236, 16, v205
	v_and_b32_e32 v237, 0xffff0000, v205
	global_load_dwordx4 v[166:169], v245, s[64:65] offset:256
	global_load_dwordx4 v[202:205], v245, s[94:95] offset:256
	v_pk_fma_f32 v[100:101], v[100:101], v[144:145], v[136:137]
	v_pk_fma_f32 v[102:103], v[102:103], v[146:147], v[138:139]
	v_pk_fma_f32 v[96:97], v[96:97], v[234:235], v[140:141]
	v_pk_fma_f32 v[98:99], v[98:99], v[236:237], v[142:143]
	s_nop 0
	v_cvt_pk_bf16_f32 v100, v100, v101
	v_cvt_pk_bf16_f32 v101, v102, v103
	v_cvt_pk_bf16_f32 v102, v96, v97
	v_cvt_pk_bf16_f32 v103, v98, v99
	s_nop 1
	v_permlane16_swap_b32_e32 v100, v102
	v_permlane16_swap_b32_e32 v101, v103
	global_store_dwordx4 v241, v[100:103], s[90:91] offset:256 sc1
	s_waitcnt vmcnt(18)
	v_permlane16_swap_b32_e32 v170, v172
	v_permlane16_swap_b32_e32 v171, v173
	v_permlane16_swap_b32_e32 v206, v208
	v_permlane16_swap_b32_e32 v207, v209
	v_lshlrev_b32_e32 v136, 16, v170
	v_and_b32_e32 v137, 0xffff0000, v170
	v_lshlrev_b32_e32 v138, 16, v171
	v_and_b32_e32 v139, 0xffff0000, v171
	v_lshlrev_b32_e32 v140, 16, v172
	v_and_b32_e32 v141, 0xffff0000, v172
	v_lshlrev_b32_e32 v142, 16, v173
	v_and_b32_e32 v143, 0xffff0000, v173
	v_lshlrev_b32_e32 v144, 16, v206
	v_and_b32_e32 v145, 0xffff0000, v206
	v_lshlrev_b32_e32 v146, 16, v207
	v_and_b32_e32 v147, 0xffff0000, v207
	v_lshlrev_b32_e32 v234, 16, v208
	v_and_b32_e32 v235, 0xffff0000, v208
	v_lshlrev_b32_e32 v236, 16, v209
	v_and_b32_e32 v237, 0xffff0000, v209
	global_load_dwordx4 v[170:173], v246, s[64:65]
	global_load_dwordx4 v[206:209], v246, s[94:95]
	v_pk_fma_f32 v[92:93], v[92:93], v[144:145], v[136:137]
	v_pk_fma_f32 v[94:95], v[94:95], v[146:147], v[138:139]
	v_pk_fma_f32 v[88:89], v[88:89], v[234:235], v[140:141]
	v_pk_fma_f32 v[90:91], v[90:91], v[236:237], v[142:143]
	s_nop 0
	v_cvt_pk_bf16_f32 v92, v92, v93
	v_cvt_pk_bf16_f32 v93, v94, v95
	v_cvt_pk_bf16_f32 v94, v88, v89
	v_cvt_pk_bf16_f32 v95, v90, v91
	s_nop 1
	v_permlane16_swap_b32_e32 v92, v94
	v_permlane16_swap_b32_e32 v93, v95
	global_store_dwordx4 v242, v[92:95], s[90:91] sc1
	s_waitcnt vmcnt(19)
	v_permlane16_swap_b32_e32 v174, v176
	v_permlane16_swap_b32_e32 v175, v177
	v_permlane16_swap_b32_e32 v210, v212
	v_permlane16_swap_b32_e32 v211, v213
	v_lshlrev_b32_e32 v136, 16, v174
	v_and_b32_e32 v137, 0xffff0000, v174
	v_lshlrev_b32_e32 v138, 16, v175
	v_and_b32_e32 v139, 0xffff0000, v175
	v_lshlrev_b32_e32 v140, 16, v176
	v_and_b32_e32 v141, 0xffff0000, v176
	v_lshlrev_b32_e32 v142, 16, v177
	v_and_b32_e32 v143, 0xffff0000, v177
	v_lshlrev_b32_e32 v144, 16, v210
	v_and_b32_e32 v145, 0xffff0000, v210
	v_lshlrev_b32_e32 v146, 16, v211
	v_and_b32_e32 v147, 0xffff0000, v211
	v_lshlrev_b32_e32 v234, 16, v212
	v_and_b32_e32 v235, 0xffff0000, v212
	v_lshlrev_b32_e32 v236, 16, v213
	v_and_b32_e32 v237, 0xffff0000, v213
	global_load_dwordx4 v[174:177], v246, s[64:65] offset:256
	global_load_dwordx4 v[210:213], v246, s[94:95] offset:256
	v_pk_fma_f32 v[84:85], v[84:85], v[144:145], v[136:137]
	v_pk_fma_f32 v[86:87], v[86:87], v[146:147], v[138:139]
	v_pk_fma_f32 v[80:81], v[80:81], v[234:235], v[140:141]
	v_pk_fma_f32 v[82:83], v[82:83], v[236:237], v[142:143]
	s_nop 0
	v_cvt_pk_bf16_f32 v84, v84, v85
	v_cvt_pk_bf16_f32 v85, v86, v87
	v_cvt_pk_bf16_f32 v86, v80, v81
	v_cvt_pk_bf16_f32 v87, v82, v83
	s_nop 1
	v_permlane16_swap_b32_e32 v84, v86
	v_permlane16_swap_b32_e32 v85, v87
	global_store_dwordx4 v242, v[84:87], s[90:91] offset:256 sc1
	s_waitcnt vmcnt(20)
	v_permlane16_swap_b32_e32 v178, v180
	v_permlane16_swap_b32_e32 v179, v181
	v_permlane16_swap_b32_e32 v214, v216
	v_permlane16_swap_b32_e32 v215, v217
	v_lshlrev_b32_e32 v136, 16, v178
	v_and_b32_e32 v137, 0xffff0000, v178
	v_lshlrev_b32_e32 v138, 16, v179
	v_and_b32_e32 v139, 0xffff0000, v179
	v_lshlrev_b32_e32 v140, 16, v180
	v_and_b32_e32 v141, 0xffff0000, v180
	v_lshlrev_b32_e32 v142, 16, v181
	v_and_b32_e32 v143, 0xffff0000, v181
	v_lshlrev_b32_e32 v144, 16, v214
	v_and_b32_e32 v145, 0xffff0000, v214
	v_lshlrev_b32_e32 v146, 16, v215
	v_and_b32_e32 v147, 0xffff0000, v215
	v_lshlrev_b32_e32 v234, 16, v216
	v_and_b32_e32 v235, 0xffff0000, v216
	v_lshlrev_b32_e32 v236, 16, v217
	v_and_b32_e32 v237, 0xffff0000, v217
	global_load_dwordx4 v[178:181], v247, s[64:65]
	global_load_dwordx4 v[214:217], v247, s[94:95]
	v_pk_fma_f32 v[76:77], v[76:77], v[144:145], v[136:137]
	v_pk_fma_f32 v[78:79], v[78:79], v[146:147], v[138:139]
	v_pk_fma_f32 v[72:73], v[72:73], v[234:235], v[140:141]
	v_pk_fma_f32 v[74:75], v[74:75], v[236:237], v[142:143]
	s_nop 0
	v_cvt_pk_bf16_f32 v76, v76, v77
	v_cvt_pk_bf16_f32 v77, v78, v79
	v_cvt_pk_bf16_f32 v78, v72, v73
	v_cvt_pk_bf16_f32 v79, v74, v75
	s_nop 1
	v_permlane16_swap_b32_e32 v76, v78
	v_permlane16_swap_b32_e32 v77, v79
	global_store_dwordx4 v243, v[76:79], s[90:91] sc1
	s_waitcnt vmcnt(21)
	v_permlane16_swap_b32_e32 v182, v184
	v_permlane16_swap_b32_e32 v183, v185
	v_permlane16_swap_b32_e32 v230, v232
	v_permlane16_swap_b32_e32 v231, v233
	v_lshlrev_b32_e32 v136, 16, v182
	v_and_b32_e32 v137, 0xffff0000, v182
	v_lshlrev_b32_e32 v138, 16, v183
	v_and_b32_e32 v139, 0xffff0000, v183
	v_lshlrev_b32_e32 v140, 16, v184
	v_and_b32_e32 v141, 0xffff0000, v184
	v_lshlrev_b32_e32 v142, 16, v185
	v_and_b32_e32 v143, 0xffff0000, v185
	v_lshlrev_b32_e32 v144, 16, v230
	v_and_b32_e32 v145, 0xffff0000, v230
	v_lshlrev_b32_e32 v146, 16, v231
	v_and_b32_e32 v147, 0xffff0000, v231
	v_lshlrev_b32_e32 v234, 16, v232
	v_and_b32_e32 v235, 0xffff0000, v232
	v_lshlrev_b32_e32 v236, 16, v233
	v_and_b32_e32 v237, 0xffff0000, v233
	global_load_dwordx4 v[182:185], v247, s[64:65] offset:256
	global_load_dwordx4 v[230:233], v247, s[94:95] offset:256
	v_pk_fma_f32 v[68:69], v[68:69], v[144:145], v[136:137]
	v_pk_fma_f32 v[70:71], v[70:71], v[146:147], v[138:139]
	v_pk_fma_f32 v[64:65], v[64:65], v[234:235], v[140:141]
	v_pk_fma_f32 v[66:67], v[66:67], v[236:237], v[142:143]
	s_nop 0
	v_cvt_pk_bf16_f32 v68, v68, v69
	v_cvt_pk_bf16_f32 v69, v70, v71
	v_cvt_pk_bf16_f32 v70, v64, v65
	v_cvt_pk_bf16_f32 v71, v66, v67
	s_nop 1
	v_permlane16_swap_b32_e32 v68, v70
	v_permlane16_swap_b32_e32 v69, v71
	global_store_dwordx4 v243, v[68:71], s[90:91] offset:256 sc1
	s_waitcnt vmcnt(22)
	v_permlane16_swap_b32_e32 v154, v156
	v_permlane16_swap_b32_e32 v155, v157
	v_permlane16_swap_b32_e32 v190, v192
	v_permlane16_swap_b32_e32 v191, v193
	v_lshlrev_b32_e32 v136, 16, v154
	v_and_b32_e32 v137, 0xffff0000, v154
	v_lshlrev_b32_e32 v138, 16, v155
	v_and_b32_e32 v139, 0xffff0000, v155
	v_lshlrev_b32_e32 v140, 16, v156
	v_and_b32_e32 v141, 0xffff0000, v156
	v_lshlrev_b32_e32 v142, 16, v157
	v_and_b32_e32 v143, 0xffff0000, v157
	v_lshlrev_b32_e32 v144, 16, v190
	v_and_b32_e32 v145, 0xffff0000, v190
	v_lshlrev_b32_e32 v146, 16, v191
	v_and_b32_e32 v147, 0xffff0000, v191
	v_lshlrev_b32_e32 v234, 16, v192
	v_and_b32_e32 v235, 0xffff0000, v192
	v_lshlrev_b32_e32 v236, 16, v193
	v_and_b32_e32 v237, 0xffff0000, v193
	v_pk_fma_f32 v[60:61], v[60:61], v[144:145], v[136:137]
	v_pk_fma_f32 v[62:63], v[62:63], v[146:147], v[138:139]
	v_pk_fma_f32 v[56:57], v[56:57], v[234:235], v[140:141]
	v_pk_fma_f32 v[58:59], v[58:59], v[236:237], v[142:143]
	s_nop 0
	v_cvt_pk_bf16_f32 v60, v60, v61
	v_cvt_pk_bf16_f32 v61, v62, v63
	v_cvt_pk_bf16_f32 v62, v56, v57
	v_cvt_pk_bf16_f32 v63, v58, v59
	s_nop 1
	v_permlane16_swap_b32_e32 v60, v62
	v_permlane16_swap_b32_e32 v61, v63
	global_store_dwordx4 v244, v[60:63], s[90:91] sc1
	s_waitcnt vmcnt(20)
	v_permlane16_swap_b32_e32 v158, v160
	v_permlane16_swap_b32_e32 v159, v161
	v_permlane16_swap_b32_e32 v194, v196
	v_permlane16_swap_b32_e32 v195, v197
	v_lshlrev_b32_e32 v136, 16, v158
	v_and_b32_e32 v137, 0xffff0000, v158
	v_lshlrev_b32_e32 v138, 16, v159
	v_and_b32_e32 v139, 0xffff0000, v159
	v_lshlrev_b32_e32 v140, 16, v160
	v_and_b32_e32 v141, 0xffff0000, v160
	v_lshlrev_b32_e32 v142, 16, v161
	v_and_b32_e32 v143, 0xffff0000, v161
	v_lshlrev_b32_e32 v144, 16, v194
	v_and_b32_e32 v145, 0xffff0000, v194
	v_lshlrev_b32_e32 v146, 16, v195
	v_and_b32_e32 v147, 0xffff0000, v195
	v_lshlrev_b32_e32 v234, 16, v196
	v_and_b32_e32 v235, 0xffff0000, v196
	v_lshlrev_b32_e32 v236, 16, v197
	v_and_b32_e32 v237, 0xffff0000, v197
	v_pk_fma_f32 v[52:53], v[52:53], v[144:145], v[136:137]
	v_pk_fma_f32 v[54:55], v[54:55], v[146:147], v[138:139]
	v_pk_fma_f32 v[48:49], v[48:49], v[234:235], v[140:141]
	v_pk_fma_f32 v[50:51], v[50:51], v[236:237], v[142:143]
	s_nop 0
	v_cvt_pk_bf16_f32 v52, v52, v53
	v_cvt_pk_bf16_f32 v53, v54, v55
	v_cvt_pk_bf16_f32 v54, v48, v49
	v_cvt_pk_bf16_f32 v55, v50, v51
	s_nop 1
	v_permlane16_swap_b32_e32 v52, v54
	v_permlane16_swap_b32_e32 v53, v55
	global_store_dwordx4 v244, v[52:55], s[90:91] offset:256 sc1
	s_waitcnt vmcnt(18)
	v_permlane16_swap_b32_e32 v162, v164
	v_permlane16_swap_b32_e32 v163, v165
	v_permlane16_swap_b32_e32 v198, v200
	v_permlane16_swap_b32_e32 v199, v201
	v_lshlrev_b32_e32 v136, 16, v162
	v_and_b32_e32 v137, 0xffff0000, v162
	v_lshlrev_b32_e32 v138, 16, v163
	v_and_b32_e32 v139, 0xffff0000, v163
	v_lshlrev_b32_e32 v140, 16, v164
	v_and_b32_e32 v141, 0xffff0000, v164
	v_lshlrev_b32_e32 v142, 16, v165
	v_and_b32_e32 v143, 0xffff0000, v165
	v_lshlrev_b32_e32 v144, 16, v198
	v_and_b32_e32 v145, 0xffff0000, v198
	v_lshlrev_b32_e32 v146, 16, v199
	v_and_b32_e32 v147, 0xffff0000, v199
	v_lshlrev_b32_e32 v234, 16, v200
	v_and_b32_e32 v235, 0xffff0000, v200
	v_lshlrev_b32_e32 v236, 16, v201
	v_and_b32_e32 v237, 0xffff0000, v201
	v_pk_fma_f32 v[44:45], v[44:45], v[144:145], v[136:137]
	v_pk_fma_f32 v[46:47], v[46:47], v[146:147], v[138:139]
	v_pk_fma_f32 v[40:41], v[40:41], v[234:235], v[140:141]
	v_pk_fma_f32 v[42:43], v[42:43], v[236:237], v[142:143]
	s_nop 0
	v_cvt_pk_bf16_f32 v44, v44, v45
	v_cvt_pk_bf16_f32 v45, v46, v47
	v_cvt_pk_bf16_f32 v46, v40, v41
	v_cvt_pk_bf16_f32 v47, v42, v43
	s_nop 1
	v_permlane16_swap_b32_e32 v44, v46
	v_permlane16_swap_b32_e32 v45, v47
	global_store_dwordx4 v245, v[44:47], s[90:91] sc1
	s_waitcnt vmcnt(16)
	v_permlane16_swap_b32_e32 v166, v168
	v_permlane16_swap_b32_e32 v167, v169
	v_permlane16_swap_b32_e32 v202, v204
	v_permlane16_swap_b32_e32 v203, v205
	v_lshlrev_b32_e32 v136, 16, v166
	v_and_b32_e32 v137, 0xffff0000, v166
	v_lshlrev_b32_e32 v138, 16, v167
	v_and_b32_e32 v139, 0xffff0000, v167
	v_lshlrev_b32_e32 v140, 16, v168
	v_and_b32_e32 v141, 0xffff0000, v168
	v_lshlrev_b32_e32 v142, 16, v169
	v_and_b32_e32 v143, 0xffff0000, v169
	v_lshlrev_b32_e32 v144, 16, v202
	v_and_b32_e32 v145, 0xffff0000, v202
	v_lshlrev_b32_e32 v146, 16, v203
	v_and_b32_e32 v147, 0xffff0000, v203
	v_lshlrev_b32_e32 v234, 16, v204
	v_and_b32_e32 v235, 0xffff0000, v204
	v_lshlrev_b32_e32 v236, 16, v205
	v_and_b32_e32 v237, 0xffff0000, v205
	v_pk_fma_f32 v[36:37], v[36:37], v[144:145], v[136:137]
	v_pk_fma_f32 v[38:39], v[38:39], v[146:147], v[138:139]
	v_pk_fma_f32 v[32:33], v[32:33], v[234:235], v[140:141]
	v_pk_fma_f32 v[34:35], v[34:35], v[236:237], v[142:143]
	s_nop 0
	v_cvt_pk_bf16_f32 v36, v36, v37
	v_cvt_pk_bf16_f32 v37, v38, v39
	v_cvt_pk_bf16_f32 v38, v32, v33
	v_cvt_pk_bf16_f32 v39, v34, v35
	s_nop 1
	v_permlane16_swap_b32_e32 v36, v38
	v_permlane16_swap_b32_e32 v37, v39
	global_store_dwordx4 v245, v[36:39], s[90:91] offset:256 sc1
	s_waitcnt vmcnt(14)
	v_permlane16_swap_b32_e32 v170, v172
	v_permlane16_swap_b32_e32 v171, v173
	v_permlane16_swap_b32_e32 v206, v208
	v_permlane16_swap_b32_e32 v207, v209
	v_lshlrev_b32_e32 v136, 16, v170
	v_and_b32_e32 v137, 0xffff0000, v170
	v_lshlrev_b32_e32 v138, 16, v171
	v_and_b32_e32 v139, 0xffff0000, v171
	v_lshlrev_b32_e32 v140, 16, v172
	v_and_b32_e32 v141, 0xffff0000, v172
	v_lshlrev_b32_e32 v142, 16, v173
	v_and_b32_e32 v143, 0xffff0000, v173
	v_lshlrev_b32_e32 v144, 16, v206
	v_and_b32_e32 v145, 0xffff0000, v206
	v_lshlrev_b32_e32 v146, 16, v207
	v_and_b32_e32 v147, 0xffff0000, v207
	v_lshlrev_b32_e32 v234, 16, v208
	v_and_b32_e32 v235, 0xffff0000, v208
	v_lshlrev_b32_e32 v236, 16, v209
	v_and_b32_e32 v237, 0xffff0000, v209
	v_pk_fma_f32 v[28:29], v[28:29], v[144:145], v[136:137]
	v_pk_fma_f32 v[30:31], v[30:31], v[146:147], v[138:139]
	v_pk_fma_f32 v[24:25], v[24:25], v[234:235], v[140:141]
	v_pk_fma_f32 v[26:27], v[26:27], v[236:237], v[142:143]
	s_nop 0
	v_cvt_pk_bf16_f32 v28, v28, v29
	v_cvt_pk_bf16_f32 v29, v30, v31
	v_cvt_pk_bf16_f32 v30, v24, v25
	v_cvt_pk_bf16_f32 v31, v26, v27
	s_nop 1
	v_permlane16_swap_b32_e32 v28, v30
	v_permlane16_swap_b32_e32 v29, v31
	global_store_dwordx4 v246, v[28:31], s[90:91] sc1
	s_waitcnt vmcnt(12)
	v_permlane16_swap_b32_e32 v174, v176
	v_permlane16_swap_b32_e32 v175, v177
	v_permlane16_swap_b32_e32 v210, v212
	v_permlane16_swap_b32_e32 v211, v213
	v_lshlrev_b32_e32 v136, 16, v174
	v_and_b32_e32 v137, 0xffff0000, v174
	v_lshlrev_b32_e32 v138, 16, v175
	v_and_b32_e32 v139, 0xffff0000, v175
	v_lshlrev_b32_e32 v140, 16, v176
	v_and_b32_e32 v141, 0xffff0000, v176
	v_lshlrev_b32_e32 v142, 16, v177
	v_and_b32_e32 v143, 0xffff0000, v177
	v_lshlrev_b32_e32 v144, 16, v210
	v_and_b32_e32 v145, 0xffff0000, v210
	v_lshlrev_b32_e32 v146, 16, v211
	v_and_b32_e32 v147, 0xffff0000, v211
	v_lshlrev_b32_e32 v234, 16, v212
	v_and_b32_e32 v235, 0xffff0000, v212
	v_lshlrev_b32_e32 v236, 16, v213
	v_and_b32_e32 v237, 0xffff0000, v213
	v_pk_fma_f32 v[20:21], v[20:21], v[144:145], v[136:137]
	v_pk_fma_f32 v[22:23], v[22:23], v[146:147], v[138:139]
	v_pk_fma_f32 v[16:17], v[16:17], v[234:235], v[140:141]
	v_pk_fma_f32 v[18:19], v[18:19], v[236:237], v[142:143]
	s_nop 0
	v_cvt_pk_bf16_f32 v20, v20, v21
	v_cvt_pk_bf16_f32 v21, v22, v23
	v_cvt_pk_bf16_f32 v22, v16, v17
	v_cvt_pk_bf16_f32 v23, v18, v19
	s_nop 1
	v_permlane16_swap_b32_e32 v20, v22
	v_permlane16_swap_b32_e32 v21, v23
	global_store_dwordx4 v246, v[20:23], s[90:91] offset:256 sc1
	s_waitcnt vmcnt(10)
	v_permlane16_swap_b32_e32 v178, v180
	v_permlane16_swap_b32_e32 v179, v181
	v_permlane16_swap_b32_e32 v214, v216
	v_permlane16_swap_b32_e32 v215, v217
	v_lshlrev_b32_e32 v136, 16, v178
	v_and_b32_e32 v137, 0xffff0000, v178
	v_lshlrev_b32_e32 v138, 16, v179
	v_and_b32_e32 v139, 0xffff0000, v179
	v_lshlrev_b32_e32 v140, 16, v180
	v_and_b32_e32 v141, 0xffff0000, v180
	v_lshlrev_b32_e32 v142, 16, v181
	v_and_b32_e32 v143, 0xffff0000, v181
	v_lshlrev_b32_e32 v144, 16, v214
	v_and_b32_e32 v145, 0xffff0000, v214
	v_lshlrev_b32_e32 v146, 16, v215
	v_and_b32_e32 v147, 0xffff0000, v215
	v_lshlrev_b32_e32 v234, 16, v216
	v_and_b32_e32 v235, 0xffff0000, v216
	v_lshlrev_b32_e32 v236, 16, v217
	v_and_b32_e32 v237, 0xffff0000, v217
	v_pk_fma_f32 v[12:13], v[12:13], v[144:145], v[136:137]
	v_pk_fma_f32 v[14:15], v[14:15], v[146:147], v[138:139]
	v_pk_fma_f32 v[8:9], v[8:9], v[234:235], v[140:141]
	v_pk_fma_f32 v[10:11], v[10:11], v[236:237], v[142:143]
	s_nop 0
	v_cvt_pk_bf16_f32 v12, v12, v13
	v_cvt_pk_bf16_f32 v13, v14, v15
	v_cvt_pk_bf16_f32 v14, v8, v9
	v_cvt_pk_bf16_f32 v15, v10, v11
	s_nop 1
	v_permlane16_swap_b32_e32 v12, v14
	v_permlane16_swap_b32_e32 v13, v15
	global_store_dwordx4 v247, v[12:15], s[90:91] sc1
	s_waitcnt vmcnt(8)
	v_permlane16_swap_b32_e32 v182, v184
	v_permlane16_swap_b32_e32 v183, v185
	v_permlane16_swap_b32_e32 v230, v232
	v_permlane16_swap_b32_e32 v231, v233
	v_lshlrev_b32_e32 v136, 16, v182
	v_and_b32_e32 v137, 0xffff0000, v182
	v_lshlrev_b32_e32 v138, 16, v183
	v_and_b32_e32 v139, 0xffff0000, v183
	v_lshlrev_b32_e32 v140, 16, v184
	v_and_b32_e32 v141, 0xffff0000, v184
	v_lshlrev_b32_e32 v142, 16, v185
	v_and_b32_e32 v143, 0xffff0000, v185
	v_lshlrev_b32_e32 v144, 16, v230
	v_and_b32_e32 v145, 0xffff0000, v230
	v_lshlrev_b32_e32 v146, 16, v231
	v_and_b32_e32 v147, 0xffff0000, v231
	v_lshlrev_b32_e32 v234, 16, v232
	v_and_b32_e32 v235, 0xffff0000, v232
	v_lshlrev_b32_e32 v236, 16, v233
	v_and_b32_e32 v237, 0xffff0000, v233
	v_pk_fma_f32 v[4:5], v[4:5], v[144:145], v[136:137]
	v_pk_fma_f32 v[6:7], v[6:7], v[146:147], v[138:139]
	v_pk_fma_f32 v[0:1], v[0:1], v[234:235], v[140:141]
	v_pk_fma_f32 v[2:3], v[2:3], v[236:237], v[142:143]
	s_nop 0
	v_cvt_pk_bf16_f32 v4, v4, v5
	v_cvt_pk_bf16_f32 v5, v6, v7
	v_cvt_pk_bf16_f32 v6, v0, v1
	v_cvt_pk_bf16_f32 v7, v2, v3
	s_nop 1
	v_permlane16_swap_b32_e32 v4, v6
	v_permlane16_swap_b32_e32 v5, v7
	global_store_dwordx4 v247, v[4:7], s[90:91] offset:256 sc1

; __device__ __forceinline__ void st_bf4(bf16_t* p, f32x4 v) { u32x2 w; w.x = pk2(v[0], v[1]); w.y = pk2(v[2], v[3]); *(u32x2*)p = w; }
; __device__ __forceinline__ float row_rstd(const float* slots, int row) {
;     const unsigned long long* sp = (const unsigned long long*)(slots + (size_t)row * 8); float t = 0.f;
; #pragma unroll
;     for (int q = 0; q < 4; ++q) { const unsigned long long w = __hip_atomic_load(sp + q, __ATOMIC_RELAXED, __HIP_MEMORY_SCOPE_AGENT); t += __uint_as_float((unsigned)w) + __uint_as_float((unsigned)(w >> 32)); }
;     return rsqrtf(t * (1.0f / DM) + EPS);
; }
; __global__ void __launch_bounds__(NTHR, 2) fwd_kernel(Args a) {
;     ...
;         { const int wid2 = __builtin_amdgcn_readfirstlane(tid2 >> 6), colg = u.pn * BM + 4 * (tid2 & 63); const float* md = mod + ((u.pm * BM) >> 11) * MODW;
;           const f32x4 gg = *(const f32x4*)(a.in[I_G2] + colg), sh = *(const f32x4*)(md + 3 * DM + colg), sc = *(const f32x4*)(md + 4 * DM + colg) + 1.0f;
; #pragma unroll
;           for (int ai = 0; ai < 2; ++ai)
; #pragma unroll
;               for (int j = 0; j < 16; ++j) { const int row = u.pm * BM + ai * HALF + wid2 * 16 + j; const float rstd = row_rstd(slots1, row);
;                   st_bf4(H2 + (size_t)row * DM + colg, (xr[ai][j] * rstd * gg) * sc + sh); }
.LBB0_1738:
	s_or_b64 exec, exec, s[2:3]
	s_waitcnt lgkmcnt(0)
	v_mov_b32_e32 v0, v189
	s_barrier
	v_readfirstlane_b32 s2, v0
	v_lshlrev_b32_e32 v0, 2, v0
	v_and_b32_e32 v0, 0xfc, v0
	v_or_b32_e32 v136, s48, v0
	v_ashrrev_i32_e32 v137, 31, v136
	v_lshlrev_b64 v[4:5], 2, v[136:137]
	v_lshl_add_u64 v[0:1], s[52:53], 0, v[4:5]
	v_lshl_add_u64 v[4:5], s[0:1], 0, v[4:5]
	s_movk_i32 s0, 0x6000
	v_add_co_u32_e32 v6, vcc, s0, v4
	s_mov_b32 s0, 0x8000
	s_nop 0
	v_addc_co_u32_e32 v7, vcc, 0, v5, vcc
	v_add_co_u32_e32 v138, vcc, s0, v4
	s_ashr_i32 s0, s2, 2
	s_and_b32 s0, s0, -16
	s_add_i32 s0, s0, s49
	v_addc_co_u32_e32 v139, vcc, 0, v5, vcc
	global_load_dwordx4 v[0:3], v[0:1], off
	global_load_dwordx4 v[4:7], v[6:7], off
	global_load_dwordx4 v[144:147], v[138:139], off
	v_lshl_add_u64 v[136:137], v[136:137], 1, s[90:91]
	v_and_b32_e32 v142, 31, v189
	v_and_b32_e32 v153, 15, v142
	v_lshrrev_b32_e32 v142, 4, v142
	v_lshl_add_u32 v153, v142, 7, v153
	v_add_u32_e32 v153, s0, v153
	v_lshlrev_b32_e32 v143, 5, v153
	global_load_dwordx4 v[148:151], v143, s[46:47] sc1
	global_load_dwordx4 v[138:141], v143, s[46:47] offset:16 sc1
	v_mov_b32_e32 v152, 0x358637bd
	s_mov_b32 s2, 0x800000
	s_waitcnt vmcnt(0)
	v_add_f32_e32 v148, v148, v149
	v_add_f32_e32 v149, v150, v151
	v_add_f32_e32 v148, 0, v148
	v_add_f32_e32 v150, v138, v139
	v_add_f32_e32 v148, v148, v149
	v_add_f32_e32 v151, v140, v141
	v_add_f32_e32 v148, v148, v150
	v_add_f32_e32 v148, v148, v151
	v_fmamk_f32 v148, v148, 0x3a000000, v152
	v_mul_f32_e32 v149, 0x4b800000, v148
	v_cmp_gt_f32_e32 vcc, s2, v148
	s_nop 1
	v_cndmask_b32_e32 v148, v148, v149, vcc
	v_rsq_f32_e32 v148, v148
	s_nop 0
	v_mul_f32_e32 v149, 0x45800000, v148
	v_cndmask_b32_e32 v143, v148, v149, vcc
	v_pk_add_f32 v[140:141], v[144:145], 1.0 op_sel_hi:[1,0]
	v_pk_add_f32 v[138:139], v[146:147], 1.0 op_sel_hi:[1,0]
	s_mov_b32 s7, 0
	v_readlane_b32 s4, v143, 0
	s_add_i32 s6, s0, 0
	s_lshl_b32 s6, s6, 12
	v_lshl_add_u64 v[148:149], v[136:137], 0, s[6:7]
	v_pk_mul_f32 v[68:69], v[68:69], s[4:5] op_sel_hi:[1,0]
	v_pk_mul_f32 v[70:71], v[70:71], s[4:5] op_sel_hi:[1,0]
	v_pk_mul_f32 v[68:69], v[2:3], v[68:69]
	v_pk_mul_f32 v[70:71], v[0:1], v[70:71]
	v_pk_fma_f32 v[68:69], v[138:139], v[68:69], v[6:7]
	v_pk_fma_f32 v[70:71], v[140:141], v[70:71], v[4:5]
	s_nop 0
	v_cvt_pk_bf16_f32 v70, v70, v71
	v_cvt_pk_bf16_f32 v71, v68, v69
	global_store_dwordx2 v[148:149], v[70:71], off sc1
	v_readlane_b32 s4, v143, 1
	s_add_i32 s6, s0, 1
	s_lshl_b32 s6, s6, 12
	v_lshl_add_u64 v[150:151], v[136:137], 0, s[6:7]
	v_pk_mul_f32 v[72:73], v[72:73], s[4:5] op_sel_hi:[1,0]
	v_pk_mul_f32 v[74:75], v[74:75], s[4:5] op_sel_hi:[1,0]
	v_pk_mul_f32 v[72:73], v[2:3], v[72:73]
	v_pk_mul_f32 v[74:75], v[0:1], v[74:75]
	v_pk_fma_f32 v[72:73], v[138:139], v[72:73], v[6:7]
	v_pk_fma_f32 v[74:75], v[140:141], v[74:75], v[4:5]
	s_nop 0
	v_cvt_pk_bf16_f32 v74, v74, v75
	v_cvt_pk_bf16_f32 v75, v72, v73
	global_store_dwordx2 v[150:151], v[74:75], off sc1
	v_readlane_b32 s4, v143, 2
	s_add_i32 s6, s0, 2
	s_lshl_b32 s6, s6, 12
	v_lshl_add_u64 v[148:149], v[136:137], 0, s[6:7]
	v_pk_mul_f32 v[76:77], v[76:77], s[4:5] op_sel_hi:[1,0]
	v_pk_mul_f32 v[78:79], v[78:79], s[4:5] op_sel_hi:[1,0]
	v_pk_mul_f32 v[76:77], v[2:3], v[76:77]
	v_pk_mul_f32 v[78:79], v[0:1], v[78:79]
	v_pk_fma_f32 v[76:77], v[138:139], v[76:77], v[6:7]
	v_pk_fma_f32 v[78:79], v[140:141], v[78:79], v[4:5]
	s_nop 0
	v_cvt_pk_bf16_f32 v78, v78, v79
	v_cvt_pk_bf16_f32 v79, v76, v77
	global_store_dwordx2 v[148:149], v[78:79], off sc1
	v_readlane_b32 s4, v143, 3
	s_add_i32 s6, s0, 3
	s_lshl_b32 s6, s6, 12
	v_lshl_add_u64 v[150:151], v[136:137], 0, s[6:7]
	v_pk_mul_f32 v[80:81], v[80:81], s[4:5] op_sel_hi:[1,0]
	v_pk_mul_f32 v[82:83], v[82:83], s[4:5] op_sel_hi:[1,0]
	v_pk_mul_f32 v[80:81], v[2:3], v[80:81]
	v_pk_mul_f32 v[82:83], v[0:1], v[82:83]
	v_pk_fma_f32 v[80:81], v[138:139], v[80:81], v[6:7]
	v_pk_fma_f32 v[82:83], v[140:141], v[82:83], v[4:5]
	s_nop 0
	v_cvt_pk_bf16_f32 v82, v82, v83
	v_cvt_pk_bf16_f32 v83, v80, v81
	global_store_dwordx2 v[150:151], v[82:83], off sc1
	v_readlane_b32 s4, v143, 4
	s_add_i32 s6, s0, 4
	s_lshl_b32 s6, s6, 12
	v_lshl_add_u64 v[148:149], v[136:137], 0, s[6:7]
	v_pk_mul_f32 v[84:85], v[84:85], s[4:5] op_sel_hi:[1,0]
	v_pk_mul_f32 v[86:87], v[86:87], s[4:5] op_sel_hi:[1,0]
	v_pk_mul_f32 v[84:85], v[2:3], v[84:85]
	v_pk_mul_f32 v[86:87], v[0:1], v[86:87]
	v_pk_fma_f32 v[84:85], v[138:139], v[84:85], v[6:7]
	v_pk_fma_f32 v[86:87], v[140:141], v[86:87], v[4:5]
	s_nop 0
	v_cvt_pk_bf16_f32 v86, v86, v87
	v_cvt_pk_bf16_f32 v87, v84, v85
	global_store_dwordx2 v[148:149], v[86:87], off sc1
	v_readlane_b32 s4, v143, 5
	s_add_i32 s6, s0, 5
	s_lshl_b32 s6, s6, 12
	v_lshl_add_u64 v[150:151], v[136:137], 0, s[6:7]
	v_pk_mul_f32 v[88:89], v[88:89], s[4:5] op_sel_hi:[1,0]
	v_pk_mul_f32 v[90:91], v[90:91], s[4:5] op_sel_hi:[1,0]
	v_pk_mul_f32 v[88:89], v[2:3], v[88:89]
	v_pk_mul_f32 v[90:91], v[0:1], v[90:91]
	v_pk_fma_f32 v[88:89], v[138:139], v[88:89], v[6:7]
	v_pk_fma_f32 v[90:91], v[140:141], v[90:91], v[4:5]
	s_nop 0
	v_cvt_pk_bf16_f32 v90, v90, v91
	v_cvt_pk_bf16_f32 v91, v88, v89
	global_store_dwordx2 v[150:151], v[90:91], off sc1
	v_readlane_b32 s4, v143, 6
	s_add_i32 s6, s0, 6
	s_lshl_b32 s6, s6, 12
	v_lshl_add_u64 v[148:149], v[136:137], 0, s[6:7]
	v_pk_mul_f32 v[92:93], v[92:93], s[4:5] op_sel_hi:[1,0]
	v_pk_mul_f32 v[94:95], v[94:95], s[4:5] op_sel_hi:[1,0]
	v_pk_mul_f32 v[92:93], v[2:3], v[92:93]
	v_pk_mul_f32 v[94:95], v[0:1], v[94:95]
	v_pk_fma_f32 v[92:93], v[138:139], v[92:93], v[6:7]
	v_pk_fma_f32 v[94:95], v[140:141], v[94:95], v[4:5]
	s_nop 0
	v_cvt_pk_bf16_f32 v94, v94, v95
; __device__ __forceinline__ void st_bf4(bf16_t* p, f32x4 v) { u32x2 w; w.x = pk2(v[0], v[1]); w.y = pk2(v[2], v[3]); *(u32x2*)p = w; }
; __global__ void __launch_bounds__(NTHR, 2) fwd_kernel(Args a) {
;     ...
;               for (int j = 0; j < 16; ++j) { const int row = u.pm * BM + ai * HALF + wid2 * 16 + j; const float rstd = row_rstd(slots1, row);
;                   st_bf4(H2 + (size_t)row * DM + colg, (xr[ai][j] * rstd * gg) * sc + sh); }
	v_cvt_pk_bf16_f32 v95, v92, v93
	global_store_dwordx2 v[148:149], v[94:95], off sc1
	v_readlane_b32 s4, v143, 7
	s_add_i32 s6, s0, 7
	s_lshl_b32 s6, s6, 12
	v_lshl_add_u64 v[150:151], v[136:137], 0, s[6:7]
	v_pk_mul_f32 v[96:97], v[96:97], s[4:5] op_sel_hi:[1,0]
	v_pk_mul_f32 v[98:99], v[98:99], s[4:5] op_sel_hi:[1,0]
	v_pk_mul_f32 v[96:97], v[2:3], v[96:97]
	v_pk_mul_f32 v[98:99], v[0:1], v[98:99]
	v_pk_fma_f32 v[96:97], v[138:139], v[96:97], v[6:7]
	v_pk_fma_f32 v[98:99], v[140:141], v[98:99], v[4:5]
	s_nop 0
	v_cvt_pk_bf16_f32 v98, v98, v99
	v_cvt_pk_bf16_f32 v99, v96, v97
	global_store_dwordx2 v[150:151], v[98:99], off sc1
	v_readlane_b32 s4, v143, 8
	s_add_i32 s6, s0, 8
	s_lshl_b32 s6, s6, 12
	v_lshl_add_u64 v[148:149], v[136:137], 0, s[6:7]
	v_pk_mul_f32 v[100:101], v[100:101], s[4:5] op_sel_hi:[1,0]
	v_pk_mul_f32 v[102:103], v[102:103], s[4:5] op_sel_hi:[1,0]
	v_pk_mul_f32 v[100:101], v[2:3], v[100:101]
	v_pk_mul_f32 v[102:103], v[0:1], v[102:103]
	v_pk_fma_f32 v[100:101], v[138:139], v[100:101], v[6:7]
	v_pk_fma_f32 v[102:103], v[140:141], v[102:103], v[4:5]
	s_nop 0
	v_cvt_pk_bf16_f32 v102, v102, v103
	v_cvt_pk_bf16_f32 v103, v100, v101
	global_store_dwordx2 v[148:149], v[102:103], off sc1
	v_readlane_b32 s4, v143, 9
	s_add_i32 s6, s0, 9
	s_lshl_b32 s6, s6, 12
	v_lshl_add_u64 v[150:151], v[136:137], 0, s[6:7]
	v_pk_mul_f32 v[104:105], v[104:105], s[4:5] op_sel_hi:[1,0]
	v_pk_mul_f32 v[106:107], v[106:107], s[4:5] op_sel_hi:[1,0]
	v_pk_mul_f32 v[104:105], v[2:3], v[104:105]
	v_pk_mul_f32 v[106:107], v[0:1], v[106:107]
	v_pk_fma_f32 v[104:105], v[138:139], v[104:105], v[6:7]
	v_pk_fma_f32 v[106:107], v[140:141], v[106:107], v[4:5]
	s_nop 0
	v_cvt_pk_bf16_f32 v106, v106, v107
	v_cvt_pk_bf16_f32 v107, v104, v105
	global_store_dwordx2 v[150:151], v[106:107], off sc1
	v_readlane_b32 s4, v143, 10
	s_add_i32 s6, s0, 10
	s_lshl_b32 s6, s6, 12
	v_lshl_add_u64 v[148:149], v[136:137], 0, s[6:7]
	v_pk_mul_f32 v[108:109], v[108:109], s[4:5] op_sel_hi:[1,0]
	v_pk_mul_f32 v[110:111], v[110:111], s[4:5] op_sel_hi:[1,0]
	v_pk_mul_f32 v[108:109], v[2:3], v[108:109]
	v_pk_mul_f32 v[110:111], v[0:1], v[110:111]
	v_pk_fma_f32 v[108:109], v[138:139], v[108:109], v[6:7]
	v_pk_fma_f32 v[110:111], v[140:141], v[110:111], v[4:5]
	s_nop 0
	v_cvt_pk_bf16_f32 v110, v110, v111
	v_cvt_pk_bf16_f32 v111, v108, v109
	global_store_dwordx2 v[148:149], v[110:111], off sc1
	v_readlane_b32 s4, v143, 11
	s_add_i32 s6, s0, 11
	s_lshl_b32 s6, s6, 12
	v_lshl_add_u64 v[150:151], v[136:137], 0, s[6:7]
	v_pk_mul_f32 v[112:113], v[112:113], s[4:5] op_sel_hi:[1,0]
	v_pk_mul_f32 v[114:115], v[114:115], s[4:5] op_sel_hi:[1,0]
	v_pk_mul_f32 v[112:113], v[2:3], v[112:113]
	v_pk_mul_f32 v[114:115], v[0:1], v[114:115]
	v_pk_fma_f32 v[112:113], v[138:139], v[112:113], v[6:7]
	v_pk_fma_f32 v[114:115], v[140:141], v[114:115], v[4:5]
	s_nop 0
	v_cvt_pk_bf16_f32 v114, v114, v115
	v_cvt_pk_bf16_f32 v115, v112, v113
	global_store_dwordx2 v[150:151], v[114:115], off sc1
	v_readlane_b32 s4, v143, 12
	s_add_i32 s6, s0, 12
	s_lshl_b32 s6, s6, 12
	v_lshl_add_u64 v[148:149], v[136:137], 0, s[6:7]
	v_pk_mul_f32 v[116:117], v[116:117], s[4:5] op_sel_hi:[1,0]
	v_pk_mul_f32 v[118:119], v[118:119], s[4:5] op_sel_hi:[1,0]
	v_pk_mul_f32 v[116:117], v[2:3], v[116:117]
	v_pk_mul_f32 v[118:119], v[0:1], v[118:119]
	v_pk_fma_f32 v[116:117], v[138:139], v[116:117], v[6:7]
	v_pk_fma_f32 v[118:119], v[140:141], v[118:119], v[4:5]
	s_nop 0
	v_cvt_pk_bf16_f32 v118, v118, v119
	v_cvt_pk_bf16_f32 v119, v116, v117
	global_store_dwordx2 v[148:149], v[118:119], off sc1
	v_readlane_b32 s4, v143, 13
	s_add_i32 s6, s0, 13
	s_lshl_b32 s6, s6, 12
	v_lshl_add_u64 v[150:151], v[136:137], 0, s[6:7]
	v_pk_mul_f32 v[120:121], v[120:121], s[4:5] op_sel_hi:[1,0]
	v_pk_mul_f32 v[122:123], v[122:123], s[4:5] op_sel_hi:[1,0]
	v_pk_mul_f32 v[120:121], v[2:3], v[120:121]
	v_pk_mul_f32 v[122:123], v[0:1], v[122:123]
	v_pk_fma_f32 v[120:121], v[138:139], v[120:121], v[6:7]
	v_pk_fma_f32 v[122:123], v[140:141], v[122:123], v[4:5]
	s_nop 0
	v_cvt_pk_bf16_f32 v122, v122, v123
	v_cvt_pk_bf16_f32 v123, v120, v121
	global_store_dwordx2 v[150:151], v[122:123], off sc1
	v_readlane_b32 s4, v143, 14
	s_add_i32 s6, s0, 14
	s_lshl_b32 s6, s6, 12
	v_lshl_add_u64 v[148:149], v[136:137], 0, s[6:7]
	v_pk_mul_f32 v[124:125], v[124:125], s[4:5] op_sel_hi:[1,0]
	v_pk_mul_f32 v[126:127], v[126:127], s[4:5] op_sel_hi:[1,0]
	v_pk_mul_f32 v[124:125], v[2:3], v[124:125]
	v_pk_mul_f32 v[126:127], v[0:1], v[126:127]
	v_pk_fma_f32 v[124:125], v[138:139], v[124:125], v[6:7]
	v_pk_fma_f32 v[126:127], v[140:141], v[126:127], v[4:5]
	s_nop 0
	v_cvt_pk_bf16_f32 v126, v126, v127
	v_cvt_pk_bf16_f32 v127, v124, v125
	global_store_dwordx2 v[148:149], v[126:127], off sc1
	v_readlane_b32 s4, v143, 15
	s_add_i32 s6, s0, 15
	s_lshl_b32 s6, s6, 12
	v_lshl_add_u64 v[150:151], v[136:137], 0, s[6:7]
	v_pk_mul_f32 v[128:129], v[128:129], s[4:5] op_sel_hi:[1,0]
	v_pk_mul_f32 v[130:131], v[130:131], s[4:5] op_sel_hi:[1,0]
	v_pk_mul_f32 v[128:129], v[2:3], v[128:129]
	v_pk_mul_f32 v[130:131], v[0:1], v[130:131]
	v_pk_fma_f32 v[128:129], v[138:139], v[128:129], v[6:7]
	v_pk_fma_f32 v[130:131], v[140:141], v[130:131], v[4:5]
	s_nop 0
	v_cvt_pk_bf16_f32 v130, v130, v131
	v_cvt_pk_bf16_f32 v131, v128, v129
	global_store_dwordx2 v[150:151], v[130:131], off sc1
	v_readlane_b32 s4, v143, 16
	s_add_i32 s6, s0, 128
	s_lshl_b32 s6, s6, 12
	v_lshl_add_u64 v[148:149], v[136:137], 0, s[6:7]
	v_pk_mul_f32 v[8:9], v[8:9], s[4:5] op_sel_hi:[1,0]
	v_pk_mul_f32 v[10:11], v[10:11], s[4:5] op_sel_hi:[1,0]
	v_pk_mul_f32 v[8:9], v[2:3], v[8:9]
	v_pk_mul_f32 v[10:11], v[0:1], v[10:11]
; __device__ __forceinline__ void st_bf4(bf16_t* p, f32x4 v) { u32x2 w; w.x = pk2(v[0], v[1]); w.y = pk2(v[2], v[3]); *(u32x2*)p = w; }
; __global__ void __launch_bounds__(NTHR, 2) fwd_kernel(Args a) {
;     ...
;               for (int j = 0; j < 16; ++j) { const int row = u.pm * BM + ai * HALF + wid2 * 16 + j; const float rstd = row_rstd(slots1, row);
;                   st_bf4(H2 + (size_t)row * DM + colg, (xr[ai][j] * rstd * gg) * sc + sh); }
	v_pk_fma_f32 v[8:9], v[138:139], v[8:9], v[6:7]
	v_pk_fma_f32 v[10:11], v[140:141], v[10:11], v[4:5]
	s_nop 0
	v_cvt_pk_bf16_f32 v10, v10, v11
	v_cvt_pk_bf16_f32 v11, v8, v9
	global_store_dwordx2 v[148:149], v[10:11], off sc1
	v_readlane_b32 s4, v143, 17
	s_add_i32 s6, s0, 129
	s_lshl_b32 s6, s6, 12
	v_lshl_add_u64 v[150:151], v[136:137], 0, s[6:7]
	v_pk_mul_f32 v[12:13], v[12:13], s[4:5] op_sel_hi:[1,0]
	v_pk_mul_f32 v[14:15], v[14:15], s[4:5] op_sel_hi:[1,0]
	v_pk_mul_f32 v[12:13], v[2:3], v[12:13]
	v_pk_mul_f32 v[14:15], v[0:1], v[14:15]
	v_pk_fma_f32 v[12:13], v[138:139], v[12:13], v[6:7]
	v_pk_fma_f32 v[14:15], v[140:141], v[14:15], v[4:5]
	s_nop 0
	v_cvt_pk_bf16_f32 v14, v14, v15
	v_cvt_pk_bf16_f32 v15, v12, v13
	global_store_dwordx2 v[150:151], v[14:15], off sc1
	v_readlane_b32 s4, v143, 18
	s_add_i32 s6, s0, 130
	s_lshl_b32 s6, s6, 12
	v_lshl_add_u64 v[148:149], v[136:137], 0, s[6:7]
	v_pk_mul_f32 v[16:17], v[16:17], s[4:5] op_sel_hi:[1,0]
	v_pk_mul_f32 v[18:19], v[18:19], s[4:5] op_sel_hi:[1,0]
	v_pk_mul_f32 v[16:17], v[2:3], v[16:17]
	v_pk_mul_f32 v[18:19], v[0:1], v[18:19]
	v_pk_fma_f32 v[16:17], v[138:139], v[16:17], v[6:7]
	v_pk_fma_f32 v[18:19], v[140:141], v[18:19], v[4:5]
	s_nop 0
	v_cvt_pk_bf16_f32 v18, v18, v19
	v_cvt_pk_bf16_f32 v19, v16, v17
	global_store_dwordx2 v[148:149], v[18:19], off sc1
	v_readlane_b32 s4, v143, 19
	s_add_i32 s6, s0, 131
	s_lshl_b32 s6, s6, 12
	v_lshl_add_u64 v[150:151], v[136:137], 0, s[6:7]
	v_pk_mul_f32 v[20:21], v[20:21], s[4:5] op_sel_hi:[1,0]
	v_pk_mul_f32 v[22:23], v[22:23], s[4:5] op_sel_hi:[1,0]
	v_pk_mul_f32 v[20:21], v[2:3], v[20:21]
	v_pk_mul_f32 v[22:23], v[0:1], v[22:23]
	v_pk_fma_f32 v[20:21], v[138:139], v[20:21], v[6:7]
	v_pk_fma_f32 v[22:23], v[140:141], v[22:23], v[4:5]
	s_nop 0
	v_cvt_pk_bf16_f32 v22, v22, v23
	v_cvt_pk_bf16_f32 v23, v20, v21
	global_store_dwordx2 v[150:151], v[22:23], off sc1
	v_readlane_b32 s4, v143, 20
	s_add_i32 s6, s0, 132
	s_lshl_b32 s6, s6, 12
	v_lshl_add_u64 v[148:149], v[136:137], 0, s[6:7]
	v_pk_mul_f32 v[24:25], v[24:25], s[4:5] op_sel_hi:[1,0]
	v_pk_mul_f32 v[26:27], v[26:27], s[4:5] op_sel_hi:[1,0]
	v_pk_mul_f32 v[24:25], v[2:3], v[24:25]
	v_pk_mul_f32 v[26:27], v[0:1], v[26:27]
	v_pk_fma_f32 v[24:25], v[138:139], v[24:25], v[6:7]
	v_pk_fma_f32 v[26:27], v[140:141], v[26:27], v[4:5]
	s_nop 0
	v_cvt_pk_bf16_f32 v26, v26, v27
	v_cvt_pk_bf16_f32 v27, v24, v25
	global_store_dwordx2 v[148:149], v[26:27], off sc1
	v_readlane_b32 s4, v143, 21
	s_add_i32 s6, s0, 133
	s_lshl_b32 s6, s6, 12
	v_lshl_add_u64 v[150:151], v[136:137], 0, s[6:7]
	v_pk_mul_f32 v[28:29], v[28:29], s[4:5] op_sel_hi:[1,0]
	v_pk_mul_f32 v[30:31], v[30:31], s[4:5] op_sel_hi:[1,0]
	v_pk_mul_f32 v[28:29], v[2:3], v[28:29]
	v_pk_mul_f32 v[30:31], v[0:1], v[30:31]
	v_pk_fma_f32 v[28:29], v[138:139], v[28:29], v[6:7]
	v_pk_fma_f32 v[30:31], v[140:141], v[30:31], v[4:5]
	s_nop 0
	v_cvt_pk_bf16_f32 v30, v30, v31
	v_cvt_pk_bf16_f32 v31, v28, v29
	global_store_dwordx2 v[150:151], v[30:31], off sc1
	v_readlane_b32 s4, v143, 22
	s_add_i32 s6, s0, 134
	s_lshl_b32 s6, s6, 12
	v_lshl_add_u64 v[148:149], v[136:137], 0, s[6:7]
	v_pk_mul_f32 v[32:33], v[32:33], s[4:5] op_sel_hi:[1,0]
	v_pk_mul_f32 v[34:35], v[34:35], s[4:5] op_sel_hi:[1,0]
	v_pk_mul_f32 v[32:33], v[2:3], v[32:33]
	v_pk_mul_f32 v[34:35], v[0:1], v[34:35]
	v_pk_fma_f32 v[32:33], v[138:139], v[32:33], v[6:7]
	v_pk_fma_f32 v[34:35], v[140:141], v[34:35], v[4:5]
	s_nop 0
	v_cvt_pk_bf16_f32 v34, v34, v35
	v_cvt_pk_bf16_f32 v35, v32, v33
	global_store_dwordx2 v[148:149], v[34:35], off sc1
	v_readlane_b32 s4, v143, 23
	s_add_i32 s6, s0, 135
	s_lshl_b32 s6, s6, 12
	v_lshl_add_u64 v[150:151], v[136:137], 0, s[6:7]
	v_pk_mul_f32 v[36:37], v[36:37], s[4:5] op_sel_hi:[1,0]
	v_pk_mul_f32 v[38:39], v[38:39], s[4:5] op_sel_hi:[1,0]
	v_pk_mul_f32 v[36:37], v[2:3], v[36:37]
	v_pk_mul_f32 v[38:39], v[0:1], v[38:39]
	v_pk_fma_f32 v[36:37], v[138:139], v[36:37], v[6:7]
	v_pk_fma_f32 v[38:39], v[140:141], v[38:39], v[4:5]
	s_nop 0
	v_cvt_pk_bf16_f32 v38, v38, v39
	v_cvt_pk_bf16_f32 v39, v36, v37
	global_store_dwordx2 v[150:151], v[38:39], off sc1
	v_readlane_b32 s4, v143, 24
	s_add_i32 s6, s0, 136
	s_lshl_b32 s6, s6, 12
	v_lshl_add_u64 v[148:149], v[136:137], 0, s[6:7]
	v_pk_mul_f32 v[40:41], v[40:41], s[4:5] op_sel_hi:[1,0]
	v_pk_mul_f32 v[42:43], v[42:43], s[4:5] op_sel_hi:[1,0]
	v_pk_mul_f32 v[40:41], v[2:3], v[40:41]
	v_pk_mul_f32 v[42:43], v[0:1], v[42:43]
	v_pk_fma_f32 v[40:41], v[138:139], v[40:41], v[6:7]
	v_pk_fma_f32 v[42:43], v[140:141], v[42:43], v[4:5]
	s_nop 0
	v_cvt_pk_bf16_f32 v42, v42, v43
	v_cvt_pk_bf16_f32 v43, v40, v41
	global_store_dwordx2 v[148:149], v[42:43], off sc1
	v_readlane_b32 s4, v143, 25
	s_add_i32 s6, s0, 137
	s_lshl_b32 s6, s6, 12
	v_lshl_add_u64 v[150:151], v[136:137], 0, s[6:7]
	v_pk_mul_f32 v[44:45], v[44:45], s[4:5] op_sel_hi:[1,0]
	v_pk_mul_f32 v[46:47], v[46:47], s[4:5] op_sel_hi:[1,0]
	v_pk_mul_f32 v[44:45], v[2:3], v[44:45]
	v_pk_mul_f32 v[46:47], v[0:1], v[46:47]
; __device__ __forceinline__ void st_bf4(bf16_t* p, f32x4 v) { u32x2 w; w.x = pk2(v[0], v[1]); w.y = pk2(v[2], v[3]); *(u32x2*)p = w; }
; __device__ __forceinline__ void xcd_barrier(const XcdBarrier& b) {
;     asm volatile("s_waitcnt vmcnt(0)" ::: "memory");
;     __syncthreads();
;     if (threadIdx.x == 0) {
;         unsigned* bar = b.bar;
;         __builtin_amdgcn_s_waitcnt(0);
;         unsigned nloc = b.st[0], nx = b.st[1];
;         if (nloc == 0u) { xcd_barrier_complete(bar, b.x, nloc, nx); b.st[0] = nloc; b.st[1] = nx; }
; __global__ void __launch_bounds__(NTHR, 2) fwd_kernel(Args a) {
;     ...
;               for (int j = 0; j < 16; ++j) { const int row = u.pm * BM + ai * HALF + wid2 * 16 + j; const float rstd = row_rstd(slots1, row);
;                   st_bf4(H2 + (size_t)row * DM + colg, (xr[ai][j] * rstd * gg) * sc + sh); }
	v_pk_fma_f32 v[44:45], v[138:139], v[44:45], v[6:7]
	v_pk_fma_f32 v[46:47], v[140:141], v[46:47], v[4:5]
	s_nop 0
	v_cvt_pk_bf16_f32 v46, v46, v47
	v_cvt_pk_bf16_f32 v47, v44, v45
	global_store_dwordx2 v[150:151], v[46:47], off sc1
	v_readlane_b32 s4, v143, 26
	s_add_i32 s6, s0, 138
	s_lshl_b32 s6, s6, 12
	v_lshl_add_u64 v[148:149], v[136:137], 0, s[6:7]
	v_pk_mul_f32 v[48:49], v[48:49], s[4:5] op_sel_hi:[1,0]
	v_pk_mul_f32 v[50:51], v[50:51], s[4:5] op_sel_hi:[1,0]
	v_pk_mul_f32 v[48:49], v[2:3], v[48:49]
	v_pk_mul_f32 v[50:51], v[0:1], v[50:51]
	v_pk_fma_f32 v[48:49], v[138:139], v[48:49], v[6:7]
	v_pk_fma_f32 v[50:51], v[140:141], v[50:51], v[4:5]
	s_nop 0
	v_cvt_pk_bf16_f32 v50, v50, v51
	v_cvt_pk_bf16_f32 v51, v48, v49
	global_store_dwordx2 v[148:149], v[50:51], off sc1
	v_readlane_b32 s4, v143, 27
	s_add_i32 s6, s0, 139
	s_lshl_b32 s6, s6, 12
	v_lshl_add_u64 v[150:151], v[136:137], 0, s[6:7]
	v_pk_mul_f32 v[52:53], v[52:53], s[4:5] op_sel_hi:[1,0]
	v_pk_mul_f32 v[54:55], v[54:55], s[4:5] op_sel_hi:[1,0]
	v_pk_mul_f32 v[52:53], v[2:3], v[52:53]
	v_pk_mul_f32 v[54:55], v[0:1], v[54:55]
	v_pk_fma_f32 v[52:53], v[138:139], v[52:53], v[6:7]
	v_pk_fma_f32 v[54:55], v[140:141], v[54:55], v[4:5]
	s_nop 0
	v_cvt_pk_bf16_f32 v54, v54, v55
	v_cvt_pk_bf16_f32 v55, v52, v53
	global_store_dwordx2 v[150:151], v[54:55], off sc1
	v_readlane_b32 s4, v143, 28
	s_add_i32 s6, s0, 140
	s_lshl_b32 s6, s6, 12
	v_lshl_add_u64 v[148:149], v[136:137], 0, s[6:7]
	v_pk_mul_f32 v[56:57], v[56:57], s[4:5] op_sel_hi:[1,0]
	v_pk_mul_f32 v[58:59], v[58:59], s[4:5] op_sel_hi:[1,0]
	v_pk_mul_f32 v[56:57], v[2:3], v[56:57]
	v_pk_mul_f32 v[58:59], v[0:1], v[58:59]
	v_pk_fma_f32 v[56:57], v[138:139], v[56:57], v[6:7]
	v_pk_fma_f32 v[58:59], v[140:141], v[58:59], v[4:5]
	s_nop 0
	v_cvt_pk_bf16_f32 v58, v58, v59
	v_cvt_pk_bf16_f32 v59, v56, v57
	global_store_dwordx2 v[148:149], v[58:59], off sc1
	v_readlane_b32 s4, v143, 29
	s_add_i32 s6, s0, 141
	s_lshl_b32 s6, s6, 12
	v_lshl_add_u64 v[150:151], v[136:137], 0, s[6:7]
	v_pk_mul_f32 v[60:61], v[60:61], s[4:5] op_sel_hi:[1,0]
	v_pk_mul_f32 v[62:63], v[62:63], s[4:5] op_sel_hi:[1,0]
	v_pk_mul_f32 v[60:61], v[2:3], v[60:61]
	v_pk_mul_f32 v[62:63], v[0:1], v[62:63]
	v_pk_fma_f32 v[60:61], v[138:139], v[60:61], v[6:7]
	v_pk_fma_f32 v[62:63], v[140:141], v[62:63], v[4:5]
	s_nop 0
	v_cvt_pk_bf16_f32 v62, v62, v63
	v_cvt_pk_bf16_f32 v63, v60, v61
	global_store_dwordx2 v[150:151], v[62:63], off sc1
	v_readlane_b32 s4, v143, 30
	s_add_i32 s6, s0, 142
	s_lshl_b32 s6, s6, 12
	v_lshl_add_u64 v[148:149], v[136:137], 0, s[6:7]
	v_pk_mul_f32 v[64:65], v[64:65], s[4:5] op_sel_hi:[1,0]
	v_pk_mul_f32 v[66:67], v[66:67], s[4:5] op_sel_hi:[1,0]
	v_pk_mul_f32 v[64:65], v[2:3], v[64:65]
	v_pk_mul_f32 v[66:67], v[0:1], v[66:67]
	v_pk_fma_f32 v[64:65], v[138:139], v[64:65], v[6:7]
	v_pk_fma_f32 v[66:67], v[140:141], v[66:67], v[4:5]
	s_nop 0
	v_cvt_pk_bf16_f32 v66, v66, v67
	v_cvt_pk_bf16_f32 v67, v64, v65
	global_store_dwordx2 v[148:149], v[66:67], off sc1
	v_readlane_b32 s4, v143, 31
	s_add_i32 s6, s0, 143
	s_lshl_b32 s6, s6, 12
	v_lshl_add_u64 v[150:151], v[136:137], 0, s[6:7]
	v_pk_mul_f32 v[132:133], v[132:133], s[4:5] op_sel_hi:[1,0]
	v_pk_mul_f32 v[134:135], v[134:135], s[4:5] op_sel_hi:[1,0]
	v_pk_mul_f32 v[132:133], v[2:3], v[132:133]
	v_pk_mul_f32 v[134:135], v[0:1], v[134:135]
	v_pk_fma_f32 v[132:133], v[138:139], v[132:133], v[6:7]
	v_pk_fma_f32 v[134:135], v[140:141], v[134:135], v[4:5]
	s_nop 0
	v_cvt_pk_bf16_f32 v134, v134, v135
	v_cvt_pk_bf16_f32 v135, v132, v133
	global_store_dwordx2 v[150:151], v[134:135], off sc1
	s_waitcnt vmcnt(0)
	s_barrier
	s_and_saveexec_b64 s[0:1], s[70:71]
	s_cbranch_execz .LBB0_1790
	s_add_i32 s2, 0, 0x20020
	v_mov_b32_e32 v0, s2
	s_waitcnt vmcnt(0) expcnt(0) lgkmcnt(0)
	ds_read_b32 v2, v0
	s_add_i32 s2, 0, 0x20024
	v_mov_b32_e32 v0, s2
	ds_read_b32 v0, v0
	s_waitcnt lgkmcnt(1)
	v_cmp_ne_u32_e32 vcc, 0, v2
	s_cbranch_vccnz .LBB0_1754
	v_readlane_b32 s2, v254, 0
	s_mul_i32 s33, s69, s2
	s_add_u32 s2, s66, 0x4200
	s_addc_u32 s3, s67, 0
	s_add_u32 s4, s66, 0x4400
	s_addc_u32 s5, s67, 0
	s_add_u32 s6, s66, 0x4500
	s_addc_u32 s7, s67, 0
	s_add_u32 s8, s66, 0x4600
	s_addc_u32 s9, s67, 0
	s_add_u32 s10, s66, 0x4700
	s_addc_u32 s11, s67, 0
	s_add_u32 s12, s66, 0x4800
	s_addc_u32 s13, s67, 0
	s_add_u32 s14, s66, 0x4900
	s_addc_u32 s15, s67, 0
	s_add_u32 s16, s66, 0x4a00
	s_addc_u32 s17, s67, 0
	s_add_u32 s18, s66, 0x4b00
	s_addc_u32 s19, s67, 0
	s_add_u32 s20, s66, 0x4c00
	s_addc_u32 s21, s67, 0
	s_add_u32 s22, s66, 0x4d00
	s_addc_u32 s23, s67, 0
	s_add_u32 s24, s66, 0x4e00
	s_addc_u32 s25, s67, 0
	s_add_u32 s26, s66, 0x4f00
	s_addc_u32 s27, s67, 0
	s_add_u32 s28, s66, 0x5000
	s_addc_u32 s29, s67, 0
	s_add_u32 s30, s66, 0x5100
	s_addc_u32 s31, s67, 0
	s_add_u32 s34, s66, 0x5200
	s_addc_u32 s35, s67, 0
	s_add_u32 s36, s66, 0x5300
	s_mul_i32 s33, s33, s68
	s_addc_u32 s37, s67, 0
	s_mov_b32 s44, 1
	v_mov_b32_e32 v16, 0
	s_branch .LBB0_1742
